# same prefetch fix in hg_item(false): next-chunk log-gate loads land in v240-247, converted at loop back-edge behind one vmcnt(0) instead of a vmcnt ladder right after issue
# speedup vs baseline: 1.0193x; 1.0066x over previous
; #define LAS __attribute__((address_space(3)))
; template <bool FULL, bool STORE = true>
; __device__ __forceinline__ void hg_item(const Prm& P, LAS unsigned char* lds, int item, int wave) {
;     ...
;         for (int g4 = 0; g4 < 4; ++g4) { const f32x4 d = *(const LAS f32x4*)(lds + HL_DC + (kb * 32 + 8 * g4 + 4 * lh) * 4);
; #pragma unroll
;             for (int i = 0; i < 2; ++i)
; #pragma unroll
;                 for (int j = 0; j < 4; ++j) S[i][4 * g4 + j] *= d[j]; }
; #pragma unroll
;         for (int ks = 0; ks < 4; ++ks) { const bf16x8 a = *(const LAS bf16x8*)(lds + HL_KDT + (kb * 32 + l31) * 144 + ks * 32 + lh * 16);
; #pragma unroll
;             for (int i = 0; i < 2; ++i) { const bf16x8 bb = *(const LAS bf16x8*)(lds + HL_IVT + ((vb0 + i) * 32 + l31) * 144 + ks * 32 + lh * 16); S[i] = __builtin_amdgcn_mfma_f32_32x32x16_bf16(a, bb, S[i], 0, 0, 0); } }
.LBB0_701:
	v_add_u32_e32 v33, s48, v67
	s_waitcnt lgkmcnt(0)
	s_barrier
	ds_read_b128 v[76:79], v33
	ds_read_b128 v[80:83], v33 offset:32
	s_add_u32 s34, s34, 0x20000
	s_addc_u32 s35, s35, 0
	s_add_u32 s26, s26, 0x10000
	s_waitcnt lgkmcnt(1)
	v_pk_mul_f32 v[16:17], v[16:17], v[76:77]
	v_pk_mul_f32 v[18:19], v[18:19], v[78:79]
	v_pk_mul_f32 v[0:1], v[0:1], v[76:77]
	v_pk_mul_f32 v[2:3], v[2:3], v[78:79]
	ds_read_b128 v[76:79], v33 offset:64
	ds_read_b128 v[84:87], v33 offset:96
	ds_read_b128 v[88:91], v73 offset:52224
	ds_read_b128 v[92:95], v74
	s_waitcnt lgkmcnt(4)
	v_pk_mul_f32 v[20:21], v[20:21], v[80:81]
	v_pk_mul_f32 v[22:23], v[22:23], v[82:83]
	v_pk_mul_f32 v[4:5], v[4:5], v[80:81]
	s_waitcnt lgkmcnt(3)
	v_pk_mul_f32 v[24:25], v[24:25], v[76:77]
	v_pk_mul_f32 v[26:27], v[26:27], v[78:79]
	s_waitcnt lgkmcnt(2)
	v_pk_mul_f32 v[28:29], v[28:29], v[84:85]
	v_pk_mul_f32 v[30:31], v[30:31], v[86:87]
	ds_read_b128 v[96:99], v73 offset:52256
	ds_read_b128 v[100:103], v74 offset:32
	v_pk_mul_f32 v[6:7], v[6:7], v[82:83]
	ds_read_b128 v[80:83], v74 offset:4608
	s_waitcnt lgkmcnt(3)
	v_mfma_f32_32x32x16_bf16 v[16:31], v[88:91], v[92:95], v[16:31]
	v_mul_f32_e64 v8, v8, v76
	v_mul_f32_e64 v9, v9, v77
	v_mul_f32_e64 v10, v10, v78
	v_mul_f32_e64 v11, v11, v79
	v_mul_f32_e64 v12, v12, v84
	v_mul_f32_e64 v13, v13, v85
	v_pk_mul_f32 v[14:15], v[14:15], v[86:87]
	ds_read_b128 v[76:79], v74 offset:4640
	s_addc_u32 s38, s38, 0
	s_cmp_eq_u32 s34, 0x200000
	s_waitcnt lgkmcnt(1)
	v_mfma_f32_32x32x16_bf16 v[0:15], v[88:91], v[80:83], v[0:15]
	v_mfma_f32_32x32x16_bf16 v[16:31], v[96:99], v[100:103], v[16:31]
	s_waitcnt lgkmcnt(0)
	v_mfma_f32_32x32x16_bf16 v[0:15], v[96:99], v[76:79], v[0:15]
	ds_read_b128 v[76:79], v73 offset:52288
	ds_read_b128 v[80:83], v74 offset:64
	ds_read_b128 v[84:87], v73 offset:52320
	ds_read_b128 v[88:91], v74 offset:96
	s_waitcnt lgkmcnt(2)
	v_mfma_f32_32x32x16_bf16 v[16:31], v[76:79], v[80:83], v[16:31]
	ds_read_b128 v[80:83], v74 offset:4672
	ds_read_b128 v[92:95], v74 offset:4704
	s_waitcnt lgkmcnt(1)
	v_mfma_f32_32x32x16_bf16 v[0:15], v[76:79], v[80:83], v[0:15]
	v_mfma_f32_32x32x16_bf16 v[16:31], v[84:87], v[88:91], v[16:31]
	s_waitcnt lgkmcnt(0)
	v_mfma_f32_32x32x16_bf16 v[0:15], v[84:87], v[92:95], v[0:15]
	s_cbranch_scc1 .LBB0_706
	s_waitcnt vmcnt(0)
	v_cvt_f32_f16_e32 v46, v240
	v_cvt_f32_f16_sdwa v47, v240 dst_sel:DWORD dst_unused:UNUSED_PAD src0_sel:WORD_1
	v_cvt_f32_f16_e32 v48, v241
	v_cvt_f32_f16_sdwa v49, v241 dst_sel:DWORD dst_unused:UNUSED_PAD src0_sel:WORD_1
	v_cvt_f32_f16_e32 v50, v242
	v_cvt_f32_f16_sdwa v51, v242 dst_sel:DWORD dst_unused:UNUSED_PAD src0_sel:WORD_1
	v_cvt_f32_f16_e32 v52, v243
	v_cvt_f32_f16_sdwa v53, v243 dst_sel:DWORD dst_unused:UNUSED_PAD src0_sel:WORD_1
	v_cvt_f32_f16_e32 v54, v244
	v_cvt_f32_f16_sdwa v55, v244 dst_sel:DWORD dst_unused:UNUSED_PAD src0_sel:WORD_1
	v_cvt_f32_f16_e32 v56, v245
	v_cvt_f32_f16_sdwa v57, v245 dst_sel:DWORD dst_unused:UNUSED_PAD src0_sel:WORD_1
	v_cvt_f32_f16_e32 v58, v246
	v_cvt_f32_f16_sdwa v59, v246 dst_sel:DWORD dst_unused:UNUSED_PAD src0_sel:WORD_1
	v_cvt_f32_f16_e32 v60, v247
	v_cvt_f32_f16_sdwa v61, v247 dst_sel:DWORD dst_unused:UNUSED_PAD src0_sel:WORD_1
	s_nop 0

; template <bool FULL, bool STORE = true>
; __device__ __forceinline__ void hg_item(const Prm& P, LAS unsigned char* lds, int item, int wave) {
;     ...
;         if (ch + 1 < 16) HG_LOADS(ch + 1);
.LBB0_704:
	s_cmp_eq_u32 s34, 0x1e0000
	s_cbranch_scc1 .LBB0_701
	v_lshl_add_u64 v[46:47], v[42:43], 0, s[34:35]
	global_load_dword v240, v[46:47], off
	v_lshl_add_u64 v[46:47], v[44:45], 0, s[34:35]
	s_or_b32 s36, s26, 0x400
	s_mov_b32 s37, s38
	global_load_dword v37, v[46:47], off
	v_lshl_add_u64 v[46:47], s[36:37], 0, v[38:39]
	v_lshlrev_b64 v[46:47], 1, v[46:47]
	v_lshl_add_u64 v[48:49], s[70:71], 0, v[46:47]
	v_lshl_add_u64 v[46:47], s[24:25], 0, v[46:47]
	s_or_b32 s36, s26, 0x800
	global_load_dword v65, v[46:47], off
	v_lshl_add_u64 v[46:47], s[36:37], 0, v[38:39]
	v_lshlrev_b64 v[46:47], 1, v[46:47]
	global_load_dword v241, v[48:49], off
	v_lshl_add_u64 v[48:49], s[70:71], 0, v[46:47]
	v_lshl_add_u64 v[46:47], s[24:25], 0, v[46:47]
	s_or_b32 s36, s26, 0xc00
	global_load_dword v68, v[46:47], off
	v_lshl_add_u64 v[46:47], s[36:37], 0, v[38:39]
	v_lshlrev_b64 v[46:47], 1, v[46:47]
	global_load_dword v242, v[48:49], off
	v_lshl_add_u64 v[48:49], s[70:71], 0, v[46:47]
	v_lshl_add_u64 v[46:47], s[24:25], 0, v[46:47]
	s_or_b32 s36, s26, 0x1000
	global_load_dword v69, v[46:47], off
	v_lshl_add_u64 v[46:47], s[36:37], 0, v[38:39]
	v_lshlrev_b64 v[46:47], 1, v[46:47]
	global_load_dword v243, v[48:49], off
	v_lshl_add_u64 v[48:49], s[70:71], 0, v[46:47]
	v_lshl_add_u64 v[46:47], s[24:25], 0, v[46:47]
	s_or_b32 s36, s26, 0x1400
	global_load_dword v70, v[46:47], off
	v_lshl_add_u64 v[46:47], s[36:37], 0, v[38:39]
	v_lshlrev_b64 v[46:47], 1, v[46:47]
	global_load_dword v244, v[48:49], off
	v_lshl_add_u64 v[48:49], s[70:71], 0, v[46:47]
	s_or_b32 s36, s26, 0x1800
	global_load_dword v245, v[48:49], off
	v_lshl_add_u64 v[48:49], s[36:37], 0, v[38:39]
	v_lshlrev_b64 v[48:49], 1, v[48:49]
	v_lshl_add_u64 v[50:51], s[70:71], 0, v[48:49]
	s_or_b32 s36, s26, 0x1c00
	global_load_dword v246, v[50:51], off
	v_lshl_add_u64 v[50:51], s[36:37], 0, v[38:39]
	v_lshlrev_b64 v[50:51], 1, v[50:51]
	v_lshl_add_u64 v[52:53], s[70:71], 0, v[50:51]
	v_lshl_add_u64 v[46:47], s[24:25], 0, v[46:47]
	global_load_dword v247, v[52:53], off
	global_load_dword v71, v[46:47], off
	v_lshl_add_u64 v[46:47], s[24:25], 0, v[48:49]
	global_load_dword v72, v[46:47], off
	v_lshl_add_u64 v[46:47], s[24:25], 0, v[50:51]
	global_load_dword v75, v[46:47], off
	s_branch .LBB0_701
